# LN loops: the two sample-row (9-row) waves of each workgroup run at s_setprio 2 so they win issue ties against their 8-row SIMD mates; prio reset at loop exit
# baseline (speedup 1.0000x reference)
.LBB0_1219:
	s_or_b64 exec, exec, s[0:1]
	s_waitcnt lgkmcnt(0)
	v_mov_b32_e32 v0, v196
	v_readlane_b32 s8, v253, 27
	s_barrier
	v_readlane_b32 s9, v253, 28
	v_readlane_b32 s10, v253, 29
	v_readlane_b32 s11, v253, 30
	v_and_b32_e32 v49, 63, v0
	v_readfirstlane_b32 s3, v0
	v_mov_b32_e32 v0, s10
	v_mov_b32_e32 v1, s11
	v_readlane_b32 s6, v255, 0
	v_readlane_b32 s8, v255, 2
	v_mov_b32_e32 v48, s94
	v_mov_b32_e32 v50, s95
	v_lshlrev_b32_e32 v144, 4, v49
	v_readlane_b32 s7, v255, 1
	v_readlane_b32 s9, v255, 3
	v_readfirstlane_b32 s0, v0
	v_readfirstlane_b32 s1, v1
	s_nop 1
	global_load_dwordx4 v[0:3], v144, s[6:7]
	global_load_dwordx4 v[4:7], v144, s[6:7] offset:1024
	global_load_dwordx4 v[8:11], v144, s[8:9]
	global_load_dwordx4 v[12:15], v144, s[8:9] offset:1024
	global_load_dwordx4 v[16:19], v144, s[6:7] offset:2048
	global_load_dwordx4 v[20:23], v144, s[6:7] offset:3072
	global_load_dwordx4 v[24:27], v144, s[8:9] offset:2048
	global_load_dwordx4 v[28:31], v144, s[8:9] offset:3072
	s_ashr_i32 s3, s3, 6
	v_readlane_b32 s6, v253, 53
	s_add_i32 s10, s6, s3
	s_ashr_i32 s11, s10, 31
	s_lshr_b32 s18, s88, 2
	s_add_i32 s18, s18, s3
	s_cmp_lt_u32 s3, 2
	s_cselect_b32 s18, s18, 0x200
	s_cbranch_scc0 .Lmy_srp_0
	s_setprio 2
.Lmy_srp_0:
	s_lshl_b64 s[6:7], s[10:11], 12
	s_add_u32 s6, s0, s6
	s_addc_u32 s7, s1, s7
	v_lshl_add_u64 v[32:33], s[6:7], 0, v[144:145]
	s_mov_b32 s3, 0x100000
	global_load_dwordx4 v[108:111], v144, s[6:7]
	global_load_dwordx4 v[104:107], v144, s[6:7] offset:1024
	global_load_dwordx4 v[100:103], v144, s[6:7] offset:2048
	global_load_dwordx4 v[88:91], v144, s[6:7] offset:3072
	s_mov_b64 s[6:7], 0x100000
	v_add_co_u32_e32 v36, vcc, s3, v32
	v_lshl_add_u64 v[44:45], v[32:33], 0, s[6:7]
	s_nop 0
	v_addc_co_u32_e32 v37, vcc, 0, v33, vcc
	global_load_dwordx4 v[32:35], v[44:45], off offset:1024
	global_load_dwordx4 v[40:43], v[44:45], off offset:2048
	s_nop 0
	global_load_dwordx4 v[36:39], v[36:37], off
	s_nop 0
	global_load_dwordx4 v[44:47], v[44:45], off offset:3072
	s_cmpk_lt_i32 s18, 0x200
	v_readfirstlane_b32 s8, v48
	s_cselect_b32 s11, 9, 8
	s_addk_i32 s18, 0x4000
	v_and_b32_e32 v53, 64, v220
	v_readfirstlane_b32 s9, v50
	s_add_u32 s19, s8, 0x306000
	v_xor_b32_e32 v51, 16, v220
	v_add_u32_e32 v53, 64, v53
	s_addc_u32 s20, s9, 0
	v_cmp_lt_i32_e32 vcc, v51, v53
	s_add_u32 s21, s8, 0x10800000
	s_addc_u32 s22, s9, 0
	v_cndmask_b32_e32 v51, v220, v51, vcc
	v_lshlrev_b32_e32 v151, 2, v51
	v_xor_b32_e32 v51, 32, v220
	v_lshlrev_b32_e32 v48, 2, v49
	v_cmp_lt_i32_e32 vcc, v51, v53
	s_add_u32 s23, s8, 0x280000
	v_lshl_add_u64 v[154:155], s[0:1], 0, v[144:145]
	v_lshlrev_b32_e32 v144, 3, v49
	v_or_b32_e32 v50, 0x100, v48
	v_or_b32_e32 v52, 0x200, v48
	v_or_b32_e32 v54, 0x300, v48
	v_cndmask_b32_e32 v51, v220, v51, vcc
	s_addc_u32 s24, s9, 0
	v_lshl_add_u64 v[56:57], s[8:9], 0, v[144:145]
	s_mov_b64 s[8:9], 0x6300000
	s_mov_b32 s3, 0
	v_lshlrev_b32_e32 v158, 2, v51
	v_cmp_eq_u32_e64 s[6:7], 0, v49
	v_lshl_add_u64 v[156:157], v[56:57], 0, s[8:9]
	v_lshlrev_b32_e32 v144, 2, v48
	v_lshlrev_b32_e32 v159, 2, v50
	v_lshlrev_b32_e32 v160, 2, v52
	v_lshlrev_b32_e32 v161, 2, v54
	s_waitcnt vmcnt(0)
	s_branch .LBB0_1221

.LBB0_1235:
	s_setprio 0
	v_mov_b32_e32 v0, s94
	v_mov_b32_e32 v1, s95
	s_getreg_b32 s3, hwreg(HW_REG_XCC_ID, 0, 4)
	s_waitcnt vmcnt(0)
	v_readfirstlane_b32 s6, v0
	v_readfirstlane_b32 s7, v1
	s_barrier
	s_and_saveexec_b64 s[0:1], s[86:87]
	s_cbranch_execz .LBB0_1287
	v_readlane_b32 s8, v254, 17
	s_waitcnt vmcnt(0) expcnt(0) lgkmcnt(0)
	s_and_b32 s3, s3, 15
	v_mov_b32_e32 v0, s8
	ds_read_b32 v2, v0
	v_readlane_b32 s8, v254, 18
	s_waitcnt lgkmcnt(0)
	v_cmp_ne_u32_e32 vcc, 0, v2
	v_mov_b32_e32 v0, s8
	ds_read_b32 v0, v0
	s_cbranch_vccnz .LBB0_1251
	s_add_u32 s8, s6, 0x1000
	s_addc_u32 s9, s7, 0
	s_add_u32 s10, s6, 0x1100
	s_addc_u32 s11, s7, 0
	s_add_u32 s12, s6, 0x1200
	s_addc_u32 s13, s7, 0
	s_add_u32 s14, s6, 0x1300
	s_addc_u32 s15, s7, 0
	s_mov_b32 s22, 1
	s_branch .LBB0_1239

.LBB0_1434:
	s_or_b64 exec, exec, s[6:7]
	s_mov_b64 s[6:7], -1
	s_and_b64 vcc, exec, s[0:1]
	s_waitcnt lgkmcnt(0)
	s_barrier
	s_cbranch_vccz .LBB0_1467
	v_mov_b32_e32 v0, v196
	v_readlane_b32 s8, v253, 27
	v_readlane_b32 s10, v253, 29
	v_readlane_b32 s11, v253, 30
	v_and_b32_e32 v37, 63, v0
	v_readfirstlane_b32 s6, v0
	v_mov_b32_e32 v0, s10
	v_mov_b32_e32 v1, s11
	v_readlane_b32 s9, v253, 28
	v_readfirstlane_b32 s12, v0
	v_readfirstlane_b32 s13, v1
	v_mov_b32_e32 v0, s94
	v_mov_b32_e32 v1, s95
	v_readlane_b32 s10, v255, 7
	v_readfirstlane_b32 s8, v0
	v_readfirstlane_b32 s9, v1
	s_add_u32 s3, s8, 0x300000
	v_readlane_b32 s14, v255, 11
	s_addc_u32 s20, s9, 0
	v_lshlrev_b32_e32 v144, 4, v37
	v_readlane_b32 s11, v255, 8
	v_readlane_b32 s15, v255, 12
	s_ashr_i32 s6, s6, 6
	v_readlane_b32 s7, v253, 53
	s_nop 1
	global_load_dwordx4 v[0:3], v144, s[10:11]
	global_load_dwordx4 v[4:7], v144, s[10:11] offset:1024
	global_load_dwordx4 v[8:11], v144, s[14:15]
	global_load_dwordx4 v[12:15], v144, s[14:15] offset:1024
	global_load_dwordx4 v[16:19], v144, s[10:11] offset:2048
	global_load_dwordx4 v[20:23], v144, s[10:11] offset:3072
	global_load_dwordx4 v[24:27], v144, s[14:15] offset:2048
	global_load_dwordx4 v[28:31], v144, s[14:15] offset:3072
	s_add_i32 s14, s7, s6
	s_ashr_i32 s15, s14, 31
	s_lshr_b32 s24, s88, 2
	s_add_i32 s24, s24, s6
	s_cmp_lt_u32 s6, 2
	s_cselect_b32 s24, s24, 0x200
	s_cbranch_scc0 .Lmy_srp_1
	s_setprio 2
.Lmy_srp_1:
	s_lshl_b64 s[6:7], s[14:15], 12
	s_add_u32 s6, s12, s6
	s_addc_u32 s7, s13, s7
	v_lshl_add_u64 v[32:33], s[6:7], 0, v[144:145]
	global_load_dwordx4 v[100:103], v144, s[6:7]
	global_load_dwordx4 v[104:107], v144, s[6:7] offset:1024
	global_load_dwordx4 v[108:111], v144, s[6:7] offset:2048
	global_load_dwordx4 v[96:99], v144, s[6:7] offset:3072
	s_mov_b64 s[6:7], 0x100000
	v_lshl_add_u64 v[34:35], v[32:33], 0, s[6:7]
	s_mov_b32 s6, 0x100000
	v_add_co_u32_e32 v32, vcc, s6, v32
	s_add_u32 s15, s8, 0x6300000
	s_nop 0
	v_addc_co_u32_e32 v33, vcc, 0, v33, vcc
	global_load_dwordx4 v[84:87], v[34:35], off offset:1024
	global_load_dwordx4 v[88:91], v[34:35], off offset:2048
	global_load_dwordx4 v[80:83], v[32:33], off
	global_load_dwordx4 v[92:95], v[34:35], off offset:3072
	v_and_b32_e32 v35, 64, v220
	v_xor_b32_e32 v33, 16, v220
	v_add_u32_e32 v35, 64, v35
	s_addc_u32 s21, s9, 0
	v_cmp_lt_i32_e32 vcc, v33, v35
	s_cmpk_lt_i32 s24, 0x200
	s_cselect_b32 s23, 9, 8
	v_cndmask_b32_e32 v33, v220, v33, vcc
	s_addk_i32 s24, 0x4000
	v_lshlrev_b32_e32 v121, 2, v33
	v_xor_b32_e32 v33, 32, v220
	v_lshlrev_b32_e32 v120, 2, v37
	v_cmp_lt_i32_e32 vcc, v33, v35
	s_add_u32 s25, s8, 0x280000
	v_or_b32_e32 v32, 0x100, v120
	v_or_b32_e32 v34, 0x200, v120
	v_or_b32_e32 v36, 0x300, v120
	v_cndmask_b32_e32 v33, v220, v33, vcc
	s_addc_u32 s26, s9, 0
	v_lshl_add_u64 v[38:39], s[8:9], 0, v[144:145]
	s_mov_b64 s[8:9], 0x10800000
	s_mov_b32 s22, 0
	v_lshlrev_b32_e32 v128, 2, v33
	v_cmp_eq_u32_e64 s[6:7], 0, v37
	v_lshl_add_u64 v[122:123], s[12:13], 0, v[144:145]
	v_lshl_add_u64 v[124:125], v[38:39], 0, s[8:9]
	v_lshlrev_b32_e32 v129, 2, v32
	v_lshlrev_b32_e32 v130, 2, v34
	v_lshlrev_b32_e32 v131, 2, v36
	s_waitcnt vmcnt(0)
	s_branch .LBB0_1437

.LBB0_1466:
	s_setprio 0
	s_mov_b64 s[6:7], 0
.LBB0_1467:
	s_and_b64 vcc, exec, s[6:7]
	s_cbranch_vccz .LBB0_1489
	v_mov_b32_e32 v0, v196
	v_readlane_b32 s8, v253, 27
	v_readlane_b32 s9, v253, 28
	v_readlane_b32 s10, v253, 29
	v_readlane_b32 s11, v253, 30
	v_and_b32_e32 v49, 63, v0
	v_readfirstlane_b32 s3, v0
	v_mov_b32_e32 v0, s10
	v_mov_b32_e32 v1, s11
	v_readlane_b32 s6, v255, 5
	v_readlane_b32 s8, v255, 9
	v_mov_b32_e32 v48, s94
	v_mov_b32_e32 v50, s95
	v_lshlrev_b32_e32 v144, 4, v49
	v_readlane_b32 s7, v255, 6
	v_readlane_b32 s9, v255, 10
	v_readfirstlane_b32 s10, v0
	v_readfirstlane_b32 s11, v1
	s_nop 1
	global_load_dwordx4 v[0:3], v144, s[6:7]
	global_load_dwordx4 v[4:7], v144, s[6:7] offset:1024
	global_load_dwordx4 v[8:11], v144, s[8:9]
	global_load_dwordx4 v[12:15], v144, s[8:9] offset:1024
	global_load_dwordx4 v[16:19], v144, s[6:7] offset:2048
	global_load_dwordx4 v[20:23], v144, s[6:7] offset:3072
	global_load_dwordx4 v[24:27], v144, s[8:9] offset:2048
	global_load_dwordx4 v[28:31], v144, s[8:9] offset:3072
	s_ashr_i32 s3, s3, 6
	v_readlane_b32 s6, v253, 53
	s_add_i32 s12, s6, s3
	s_ashr_i32 s13, s12, 31
	s_lshr_b32 s20, s88, 2
	s_add_i32 s20, s20, s3
	s_cmp_lt_u32 s3, 2
	s_cselect_b32 s20, s20, 0x200
	s_cbranch_scc0 .Lmy_srp_2
	s_setprio 2
.Lmy_srp_2:
	s_lshl_b64 s[6:7], s[12:13], 12
	s_add_u32 s6, s10, s6
	s_addc_u32 s7, s11, s7
	s_waitcnt vmcnt(13)
	v_lshl_add_u64 v[32:33], s[6:7], 0, v[144:145]
	s_mov_b32 s3, 0x100000
	global_load_dwordx4 v[100:103], v144, s[6:7]
	global_load_dwordx4 v[104:107], v144, s[6:7] offset:1024
	global_load_dwordx4 v[108:111], v144, s[6:7] offset:2048
	global_load_dwordx4 v[88:91], v144, s[6:7] offset:3072
	s_mov_b64 s[6:7], 0x100000
	s_waitcnt vmcnt(15)
	v_add_co_u32_e32 v36, vcc, s3, v32
	v_lshl_add_u64 v[44:45], v[32:33], 0, s[6:7]
	s_nop 0
	v_addc_co_u32_e32 v37, vcc, 0, v33, vcc
	global_load_dwordx4 v[32:35], v[44:45], off offset:1024
	global_load_dwordx4 v[40:43], v[44:45], off offset:2048
	s_nop 0
	global_load_dwordx4 v[36:39], v[36:37], off
	s_nop 0
	global_load_dwordx4 v[44:47], v[44:45], off offset:3072
	v_and_b32_e32 v53, 64, v220
	s_cmpk_lt_i32 s20, 0x200
	v_xor_b32_e32 v51, 16, v220
	v_add_u32_e32 v53, 64, v53
	v_readfirstlane_b32 s8, v48
	s_cselect_b32 s13, 9, 8
	s_addk_i32 s20, 0x4000
	v_cmp_lt_i32_e32 vcc, v51, v53
	v_readfirstlane_b32 s9, v50
	s_add_u32 s21, s8, 0x303000
	v_cndmask_b32_e32 v51, v220, v51, vcc
	s_addc_u32 s22, s9, 0
	v_lshlrev_b32_e32 v128, 2, v51
	v_xor_b32_e32 v51, 32, v220
	v_lshlrev_b32_e32 v56, 3, v49
	v_mov_b32_e32 v57, v145
	v_lshlrev_b32_e32 v48, 2, v49
	v_cmp_lt_i32_e32 vcc, v51, v53
	s_add_u32 s23, s8, 0x280000
	v_lshl_add_u64 v[56:57], s[8:9], 0, v[56:57]
	s_mov_b64 s[14:15], 0x6300000
	v_or_b32_e32 v50, 0x100, v48
	v_or_b32_e32 v52, 0x200, v48
	v_or_b32_e32 v54, 0x300, v48
	v_cndmask_b32_e32 v51, v220, v51, vcc
	s_addc_u32 s24, s9, 0
	v_lshl_add_u64 v[122:123], v[56:57], 0, s[14:15]
	v_lshl_add_u64 v[56:57], s[8:9], 0, v[144:145]
	s_mov_b64 s[8:9], 0x10800000
	s_mov_b32 s3, 0
	v_lshlrev_b32_e32 v129, 2, v51
	v_cmp_eq_u32_e64 s[6:7], 0, v49
	v_lshl_add_u64 v[120:121], s[10:11], 0, v[144:145]
	v_lshl_add_u64 v[124:125], v[56:57], 0, s[8:9]
	v_lshlrev_b32_e32 v130, 2, v48
	v_lshlrev_b32_e32 v131, 2, v50
	v_lshlrev_b32_e32 v132, 2, v52
	v_lshlrev_b32_e32 v133, 2, v54
	s_waitcnt vmcnt(0)
	s_branch .LBB0_1470

.LBB0_1489:
	s_setprio 0
	v_readlane_b32 s6, v254, 23
	v_readlane_b32 s8, v255, 19
	v_readlane_b32 s7, v254, 24
	v_readlane_b32 s9, v255, 20
	s_and_b64 s[6:7], s[6:7], s[8:9]
	s_and_b64 vcc, exec, s[6:7]
	s_cbranch_vccnz .LBB0_411
	v_mov_b32_e32 v0, s94
	v_mov_b32_e32 v1, s95
	s_getreg_b32 s3, hwreg(HW_REG_XCC_ID, 0, 4)
	s_waitcnt vmcnt(0)
	v_readfirstlane_b32 s8, v0
	v_readfirstlane_b32 s9, v1
	s_barrier
	s_and_saveexec_b64 s[6:7], s[86:87]
	s_cbranch_execz .LBB0_410
	v_readlane_b32 s10, v254, 17
	s_waitcnt vmcnt(0) expcnt(0) lgkmcnt(0)
	s_and_b32 s3, s3, 15
	v_mov_b32_e32 v0, s10
	ds_read_b32 v2, v0
	v_readlane_b32 s10, v254, 18
	s_waitcnt lgkmcnt(0)
	v_cmp_ne_u32_e32 vcc, 0, v2
	v_mov_b32_e32 v0, s10
	ds_read_b32 v0, v0
	s_cbranch_vccnz .LBB0_1506
	s_add_u32 s10, s8, 0x1000
	s_addc_u32 s11, s9, 0
	s_add_u32 s12, s8, 0x1100
	s_addc_u32 s13, s9, 0
	s_add_u32 s14, s8, 0x1200
	s_addc_u32 s15, s9, 0
	s_add_u32 s16, s8, 0x1300
	s_addc_u32 s17, s9, 0
	s_mov_b32 s24, 1
	s_branch .LBB0_1494
